# MLA: each staging register refilled (next tile's load) right after its LDS write
# baseline (speedup 1.0000x reference)
.Lmla_x_cont0:
	v_exp_f32_e32 v116, v116
	v_exp_f32_e32 v117, v117
	v_exp_f32_e32 v118, v118
	v_exp_f32_e32 v119, v119
	v_exp_f32_e32 v132, v132
	v_exp_f32_e32 v133, v133
	v_exp_f32_e32 v134, v134
	v_exp_f32_e32 v135, v135
	s_waitcnt lgkmcnt(8)
	v_exp_f32_e32 v120, v120
	v_mfma_f32_16x16x32_bf16 v[176:179], v[4:7], v[8:11], v[108:111]
	v_exp_f32_e32 v121, v121
	v_mfma_f32_16x16x32_bf16 v[192:195], v[4:7], v[40:43], v[112:115]
	v_exp_f32_e32 v122, v122
	v_mfma_f32_16x16x32_bf16 v[176:179], v[12:15], v[32:35], v[176:179]
	v_exp_f32_e32 v123, v123
	v_mfma_f32_16x16x32_bf16 v[192:195], v[12:15], v[44:47], v[192:195]
	v_exp_f32_e32 v136, v136
	v_mfma_f32_16x16x32_bf16 v[176:179], v[20:23], v[36:39], v[176:179]
	v_exp_f32_e32 v137, v137
	v_mfma_f32_16x16x32_bf16 v[192:195], v[20:23], v[16:19], v[192:195]
	v_exp_f32_e32 v138, v138
	v_exp_f32_e32 v139, v139
	ds_read_b128 v[4:7], v175 offset:21504
	ds_read_b128 v[12:15], v175 offset:25600
	ds_read_b128 v[20:23], v175 offset:29696
	v_cvt_pk_bf16_f32 v116, v116, v117
	v_cvt_pk_bf16_f32 v117, v118, v119
	v_cvt_pk_bf16_f32 v118, v120, v121
	v_cvt_pk_bf16_f32 v119, v122, v123
	v_cvt_pk_bf16_f32 v132, v132, v133
	v_cvt_pk_bf16_f32 v133, v134, v135
	v_cvt_pk_bf16_f32 v134, v136, v137
	v_cvt_pk_bf16_f32 v135, v138, v139
	s_waitcnt lgkmcnt(0)
	v_exp_f32_e32 v124, v124
	v_mfma_f32_16x16x32_bf16 v[180:183], v[4:7], v[8:11], v[108:111]
	v_exp_f32_e32 v125, v125
	v_mfma_f32_16x16x32_bf16 v[196:199], v[4:7], v[40:43], v[112:115]
	v_exp_f32_e32 v126, v126
	v_mfma_f32_16x16x32_bf16 v[180:183], v[12:15], v[32:35], v[180:183]
	v_exp_f32_e32 v127, v127
	v_mfma_f32_16x16x32_bf16 v[196:199], v[12:15], v[44:47], v[196:199]
	v_exp_f32_e32 v140, v140
	v_mfma_f32_16x16x32_bf16 v[180:183], v[20:23], v[36:39], v[180:183]
	v_exp_f32_e32 v141, v141
	v_mfma_f32_16x16x32_bf16 v[196:199], v[20:23], v[16:19], v[196:199]
	v_exp_f32_e32 v142, v142
	v_exp_f32_e32 v143, v143
	ds_read_b128 v[4:7], v175 offset:22528
	ds_read_b128 v[12:15], v175 offset:26624
	ds_read_b128 v[20:23], v175 offset:30720
	ds_read_b64_tr_b16 v[208:209], v167 offset:16384
	ds_read_b64_tr_b16 v[210:211], v167 offset:18432
	ds_read_b64_tr_b16 v[240:241], v171 offset:16384
	ds_read_b64_tr_b16 v[242:243], v171 offset:18432
	ds_read_b64_tr_b16 v[252:253], v172 offset:16384
	ds_read_b64_tr_b16 v[254:255], v172 offset:18432
	s_setprio 0
	v_mfma_f32_16x16x32_bf16 v[104:107], v[248:251], v[116:119], v[104:107]
	v_exp_f32_e32 v128, v128
	v_mfma_f32_16x16x32_bf16 v[88:91], v[248:251], v[132:135], v[88:91]
	v_exp_f32_e32 v129, v129
	v_mfma_f32_16x16x32_bf16 v[100:103], v[24:27], v[116:119], v[100:103]
	v_exp_f32_e32 v130, v130
	v_mfma_f32_16x16x32_bf16 v[80:83], v[24:27], v[132:135], v[80:83]
	v_exp_f32_e32 v131, v131
	v_mfma_f32_16x16x32_bf16 v[96:99], v[28:31], v[116:119], v[96:99]
	v_exp_f32_e32 v144, v144
	v_mfma_f32_16x16x32_bf16 v[76:79], v[28:31], v[132:135], v[76:79]
	v_exp_f32_e32 v145, v145
	s_waitcnt lgkmcnt(6)
	v_mfma_f32_16x16x32_bf16 v[184:187], v[4:7], v[8:11], v[108:111]
	v_exp_f32_e32 v146, v146
	v_exp_f32_e32 v147, v147
	v_mfma_f32_16x16x32_bf16 v[200:203], v[4:7], v[40:43], v[112:115]
	s_nop 0
	v_cvt_pk_bf16_f32 v124, v124, v125
	v_mfma_f32_16x16x32_bf16 v[184:187], v[12:15], v[32:35], v[184:187]
	v_cvt_pk_bf16_f32 v125, v126, v127
	v_cvt_pk_bf16_f32 v126, v128, v129
	v_mfma_f32_16x16x32_bf16 v[200:203], v[12:15], v[44:47], v[200:203]
	v_cvt_pk_bf16_f32 v127, v130, v131
	v_cvt_pk_bf16_f32 v140, v140, v141
	v_mfma_f32_16x16x32_bf16 v[184:187], v[20:23], v[36:39], v[184:187]
	v_cvt_pk_bf16_f32 v141, v142, v143
	v_cvt_pk_bf16_f32 v142, v144, v145
	v_mfma_f32_16x16x32_bf16 v[200:203], v[20:23], v[16:19], v[200:203]
	v_cvt_pk_bf16_f32 v143, v146, v147
	ds_read_b128 v[4:7], v175 offset:23552
	ds_read_b128 v[12:15], v175 offset:27648
	ds_read_b128 v[20:23], v175 offset:31744
	ds_read_b64_tr_b16 v[24:25], v173 offset:16384
	ds_read_b64_tr_b16 v[26:27], v173 offset:18432
	v_mfma_f32_16x16x32_bf16 v[92:95], v[148:151], v[116:119], v[92:95]
	v_mfma_f32_16x16x32_bf16 v[72:75], v[148:151], v[132:135], v[72:75]
	v_mfma_f32_16x16x32_bf16 v[84:87], v[152:155], v[116:119], v[84:87]
	v_mfma_f32_16x16x32_bf16 v[68:71], v[152:155], v[132:135], v[68:71]
	s_waitcnt lgkmcnt(2)
	v_mfma_f32_16x16x32_bf16 v[188:191], v[4:7], v[8:11], v[108:111]
	s_waitcnt vmcnt(3)
	ds_write_b128 v170, v[48:51] offset:32768
	ds_write_b128 v170, v[64:67] offset:36864
	v_mfma_f32_16x16x32_bf16 v[204:207], v[4:7], v[40:43], v[112:115]
	global_load_dwordx4 v[48:51], v[164:165], off offset:128
	s_mov_b64 s[0:1], 0x10000
	v_lshl_add_u64 v[212:213], v[164:165], 0, s[0:1]
	v_mfma_f32_16x16x32_bf16 v[188:191], v[12:15], v[32:35], v[188:191]
	global_load_dwordx4 v[64:67], v[212:213], off offset:128
	s_mov_b64 s[0:1], 0x20000
	v_lshl_add_u64 v[164:165], v[164:165], 0, s[0:1]
	v_mfma_f32_16x16x32_bf16 v[204:207], v[12:15], v[44:47], v[204:207]
	s_waitcnt vmcnt(4)
	ds_write_b128 v168, v[56:59] offset:0
	global_load_dwordx4 v[56:59], v[164:165], off
	v_mfma_f32_16x16x32_bf16 v[188:191], v[20:23], v[36:39], v[188:191]
	s_mov_b64 s[0:1], 0x10000
	v_lshl_add_u64 v[212:213], v[164:165], 0, s[0:1]
	s_waitcnt vmcnt(4)
	v_mfma_f32_16x16x32_bf16 v[204:207], v[20:23], v[16:19], v[204:207]
	ds_write_b128 v168, v[60:63] offset:2048
	global_load_dwordx4 v[60:63], v[212:213], off
	s_waitcnt vmcnt(4)
	ds_write_b128 v169, v[52:55] offset:8192
	global_load_dwordx4 v[52:55], v[160:161], off
	s_mov_b64 s[0:1], 0xe4000
	v_lshl_add_u64 v[160:161], v[160:161], 0, s[0:1]
	v_mfma_f32_16x16x32_bf16 v[104:107], v[248:251], v[124:127], v[104:107]
	v_max3_f32 v2, v176, v177, v178
	v_max3_f32 v3, v192, v193, v194
	v_mfma_f32_16x16x32_bf16 v[88:91], v[248:251], v[140:143], v[88:91]
	v_max3_f32 v2, v2, v179, v180
	v_max3_f32 v3, v3, v195, v196
	v_mfma_f32_16x16x32_bf16 v[100:103], v[208:211], v[124:127], v[100:103]
	v_max3_f32 v2, v2, v181, v182
	v_max3_f32 v3, v3, v197, v198
	v_mfma_f32_16x16x32_bf16 v[80:83], v[208:211], v[140:143], v[80:83]
	v_max3_f32 v2, v2, v183, v184
	v_max3_f32 v3, v3, v199, v200
	v_mfma_f32_16x16x32_bf16 v[96:99], v[240:243], v[124:127], v[96:99]
	v_max3_f32 v2, v2, v185, v186
	v_max3_f32 v3, v3, v201, v202
	v_mfma_f32_16x16x32_bf16 v[76:79], v[240:243], v[140:143], v[76:79]
	v_max3_f32 v2, v2, v187, v188
	v_max3_f32 v3, v3, v203, v204
	v_mfma_f32_16x16x32_bf16 v[92:95], v[252:255], v[124:127], v[92:95]
	v_max3_f32 v2, v2, v189, v190
	v_max3_f32 v3, v3, v205, v206
	v_mfma_f32_16x16x32_bf16 v[72:75], v[252:255], v[140:143], v[72:75]
	v_max3_f32 v2, v2, v191, v191
	v_max3_f32 v3, v3, v207, v207
	s_waitcnt lgkmcnt(0)
	v_mfma_f32_16x16x32_bf16 v[84:87], v[24:27], v[124:127], v[84:87]
	v_mfma_f32_16x16x32_bf16 v[68:71], v[24:27], v[140:143], v[68:71]
	s_add_i32 s57, s57, 1
	s_cmp_lt_u32 s57, s44
	s_barrier
	s_setprio 2
	s_cbranch_scc0 .Lmla_x_done

.Lmla_x_cont1:
	v_exp_f32_e32 v176, v176
	v_exp_f32_e32 v177, v177
	v_exp_f32_e32 v178, v178
	v_exp_f32_e32 v179, v179
	v_exp_f32_e32 v192, v192
	v_exp_f32_e32 v193, v193
	v_exp_f32_e32 v194, v194
	v_exp_f32_e32 v195, v195
	s_waitcnt lgkmcnt(8)
	v_exp_f32_e32 v180, v180
	v_mfma_f32_16x16x32_bf16 v[116:119], v[4:7], v[8:11], v[108:111]
	v_exp_f32_e32 v181, v181
	v_mfma_f32_16x16x32_bf16 v[132:135], v[4:7], v[40:43], v[112:115]
	v_exp_f32_e32 v182, v182
	v_mfma_f32_16x16x32_bf16 v[116:119], v[12:15], v[32:35], v[116:119]
	v_exp_f32_e32 v183, v183
	v_mfma_f32_16x16x32_bf16 v[132:135], v[12:15], v[44:47], v[132:135]
	v_exp_f32_e32 v196, v196
	v_mfma_f32_16x16x32_bf16 v[116:119], v[20:23], v[36:39], v[116:119]
	v_exp_f32_e32 v197, v197
	v_mfma_f32_16x16x32_bf16 v[132:135], v[20:23], v[16:19], v[132:135]
	v_exp_f32_e32 v198, v198
	v_exp_f32_e32 v199, v199
	ds_read_b128 v[4:7], v175 offset:1024
	ds_read_b128 v[12:15], v175 offset:5120
	ds_read_b128 v[20:23], v175 offset:9216
	v_cvt_pk_bf16_f32 v176, v176, v177
	v_cvt_pk_bf16_f32 v177, v178, v179
	v_cvt_pk_bf16_f32 v178, v180, v181
	v_cvt_pk_bf16_f32 v179, v182, v183
	v_cvt_pk_bf16_f32 v192, v192, v193
	v_cvt_pk_bf16_f32 v193, v194, v195
	v_cvt_pk_bf16_f32 v194, v196, v197
	v_cvt_pk_bf16_f32 v195, v198, v199
	s_waitcnt lgkmcnt(0)
	v_exp_f32_e32 v184, v184
	v_mfma_f32_16x16x32_bf16 v[120:123], v[4:7], v[8:11], v[108:111]
	v_exp_f32_e32 v185, v185
	v_mfma_f32_16x16x32_bf16 v[136:139], v[4:7], v[40:43], v[112:115]
	v_exp_f32_e32 v186, v186
	v_mfma_f32_16x16x32_bf16 v[120:123], v[12:15], v[32:35], v[120:123]
	v_exp_f32_e32 v187, v187
	v_mfma_f32_16x16x32_bf16 v[136:139], v[12:15], v[44:47], v[136:139]
	v_exp_f32_e32 v200, v200
	v_mfma_f32_16x16x32_bf16 v[120:123], v[20:23], v[36:39], v[120:123]
	v_exp_f32_e32 v201, v201
	v_mfma_f32_16x16x32_bf16 v[136:139], v[20:23], v[16:19], v[136:139]
	v_exp_f32_e32 v202, v202
	v_exp_f32_e32 v203, v203
	ds_read_b128 v[4:7], v175 offset:2048
	ds_read_b128 v[12:15], v175 offset:6144
	ds_read_b128 v[20:23], v175 offset:10240
	ds_read_b64_tr_b16 v[208:209], v167 offset:36864
	ds_read_b64_tr_b16 v[210:211], v167 offset:38912
	ds_read_b64_tr_b16 v[240:241], v171 offset:36864
	ds_read_b64_tr_b16 v[242:243], v171 offset:38912
	ds_read_b64_tr_b16 v[252:253], v172 offset:36864
	ds_read_b64_tr_b16 v[254:255], v172 offset:38912
	s_setprio 0
	v_mfma_f32_16x16x32_bf16 v[104:107], v[248:251], v[176:179], v[104:107]
	v_exp_f32_e32 v188, v188
	v_mfma_f32_16x16x32_bf16 v[88:91], v[248:251], v[192:195], v[88:91]
	v_exp_f32_e32 v189, v189
	v_mfma_f32_16x16x32_bf16 v[100:103], v[24:27], v[176:179], v[100:103]
	v_exp_f32_e32 v190, v190
	v_mfma_f32_16x16x32_bf16 v[80:83], v[24:27], v[192:195], v[80:83]
	v_exp_f32_e32 v191, v191
	v_mfma_f32_16x16x32_bf16 v[96:99], v[28:31], v[176:179], v[96:99]
	v_exp_f32_e32 v204, v204
	v_mfma_f32_16x16x32_bf16 v[76:79], v[28:31], v[192:195], v[76:79]
	v_exp_f32_e32 v205, v205
	s_waitcnt lgkmcnt(6)
	v_mfma_f32_16x16x32_bf16 v[124:127], v[4:7], v[8:11], v[108:111]
	v_exp_f32_e32 v206, v206
	v_exp_f32_e32 v207, v207
	v_mfma_f32_16x16x32_bf16 v[140:143], v[4:7], v[40:43], v[112:115]
	s_nop 0
	v_cvt_pk_bf16_f32 v184, v184, v185
	v_mfma_f32_16x16x32_bf16 v[124:127], v[12:15], v[32:35], v[124:127]
	v_cvt_pk_bf16_f32 v185, v186, v187
	v_cvt_pk_bf16_f32 v186, v188, v189
	v_mfma_f32_16x16x32_bf16 v[140:143], v[12:15], v[44:47], v[140:143]
	v_cvt_pk_bf16_f32 v187, v190, v191
	v_cvt_pk_bf16_f32 v200, v200, v201
	v_mfma_f32_16x16x32_bf16 v[124:127], v[20:23], v[36:39], v[124:127]
	v_cvt_pk_bf16_f32 v201, v202, v203
	v_cvt_pk_bf16_f32 v202, v204, v205
	v_mfma_f32_16x16x32_bf16 v[140:143], v[20:23], v[16:19], v[140:143]
	v_cvt_pk_bf16_f32 v203, v206, v207
	ds_read_b128 v[4:7], v175 offset:3072
	ds_read_b128 v[12:15], v175 offset:7168
	ds_read_b128 v[20:23], v175 offset:11264
	ds_read_b64_tr_b16 v[24:25], v173 offset:36864
	ds_read_b64_tr_b16 v[26:27], v173 offset:38912
	v_mfma_f32_16x16x32_bf16 v[92:95], v[148:151], v[176:179], v[92:95]
	v_mfma_f32_16x16x32_bf16 v[72:75], v[148:151], v[192:195], v[72:75]
	v_mfma_f32_16x16x32_bf16 v[84:87], v[152:155], v[176:179], v[84:87]
	v_mfma_f32_16x16x32_bf16 v[68:71], v[152:155], v[192:195], v[68:71]
	s_waitcnt lgkmcnt(2)
	v_mfma_f32_16x16x32_bf16 v[128:131], v[4:7], v[8:11], v[108:111]
	s_waitcnt vmcnt(3)
	ds_write_b128 v170, v[48:51] offset:12288
	ds_write_b128 v170, v[64:67] offset:16384
	v_mfma_f32_16x16x32_bf16 v[144:147], v[4:7], v[40:43], v[112:115]
	global_load_dwordx4 v[48:51], v[164:165], off offset:128
	s_mov_b64 s[0:1], 0x10000
	v_lshl_add_u64 v[212:213], v[164:165], 0, s[0:1]
	v_mfma_f32_16x16x32_bf16 v[128:131], v[12:15], v[32:35], v[128:131]
	global_load_dwordx4 v[64:67], v[212:213], off offset:128
	s_mov_b64 s[0:1], 0x20000
	v_lshl_add_u64 v[164:165], v[164:165], 0, s[0:1]
	v_mfma_f32_16x16x32_bf16 v[144:147], v[12:15], v[44:47], v[144:147]
	s_waitcnt vmcnt(4)
	ds_write_b128 v168, v[56:59] offset:20480
	global_load_dwordx4 v[56:59], v[164:165], off
	v_mfma_f32_16x16x32_bf16 v[128:131], v[20:23], v[36:39], v[128:131]
	s_mov_b64 s[0:1], 0x10000
	v_lshl_add_u64 v[212:213], v[164:165], 0, s[0:1]
	s_waitcnt vmcnt(4)
	v_mfma_f32_16x16x32_bf16 v[144:147], v[20:23], v[16:19], v[144:147]
	ds_write_b128 v168, v[60:63] offset:22528
	global_load_dwordx4 v[60:63], v[212:213], off
	s_waitcnt vmcnt(4)
	ds_write_b128 v169, v[52:55] offset:28672
	global_load_dwordx4 v[52:55], v[160:161], off
	s_mov_b64 s[0:1], 0xe4000
	v_lshl_add_u64 v[160:161], v[160:161], 0, s[0:1]
	v_mfma_f32_16x16x32_bf16 v[104:107], v[248:251], v[184:187], v[104:107]
	v_max3_f32 v2, v116, v117, v118
	v_max3_f32 v3, v132, v133, v134
	v_mfma_f32_16x16x32_bf16 v[88:91], v[248:251], v[200:203], v[88:91]
	v_max3_f32 v2, v2, v119, v120
	v_max3_f32 v3, v3, v135, v136
	v_mfma_f32_16x16x32_bf16 v[100:103], v[208:211], v[184:187], v[100:103]
	v_max3_f32 v2, v2, v121, v122
	v_max3_f32 v3, v3, v137, v138
	v_mfma_f32_16x16x32_bf16 v[80:83], v[208:211], v[200:203], v[80:83]
	v_max3_f32 v2, v2, v123, v124
	v_max3_f32 v3, v3, v139, v140
	v_mfma_f32_16x16x32_bf16 v[96:99], v[240:243], v[184:187], v[96:99]
	v_max3_f32 v2, v2, v125, v126
	v_max3_f32 v3, v3, v141, v142
	v_mfma_f32_16x16x32_bf16 v[76:79], v[240:243], v[200:203], v[76:79]
	v_max3_f32 v2, v2, v127, v128
	v_max3_f32 v3, v3, v143, v144
	v_mfma_f32_16x16x32_bf16 v[92:95], v[252:255], v[184:187], v[92:95]
	v_max3_f32 v2, v2, v129, v130
	v_max3_f32 v3, v3, v145, v146
	v_mfma_f32_16x16x32_bf16 v[72:75], v[252:255], v[200:203], v[72:75]
	v_max3_f32 v2, v2, v131, v131
	v_max3_f32 v3, v3, v147, v147
	s_waitcnt lgkmcnt(0)
	v_mfma_f32_16x16x32_bf16 v[84:87], v[24:27], v[184:187], v[84:87]
	v_mfma_f32_16x16x32_bf16 v[68:71], v[24:27], v[200:203], v[68:71]
	s_add_i32 s57, s57, 1
	s_cmp_lt_u32 s57, s44
	s_barrier
	s_setprio 2
	s_cbranch_scc1 .Lmla_x_body0
